# S5 pass A rewritten: B*u on f32 matrix cores (v_mfma_f32_32x32x2_f32, exact f32) + blocked complex scan, no LDS staging/barriers
# speedup vs baseline: 1.0094x; 1.0094x over previous
.LBB0_283:
	s_or_b64 exec, exec, s[6:7]
	s_add_u32 s10, s74, 0x12cd5c00
	s_addc_u32 s11, s75, 0
	s_add_u32 s24, s74, 0x12ce5c00
	s_addc_u32 s25, s75, 0
	s_add_u32 s26, s74, 0x12d25c00
	s_addc_u32 s27, s75, 0
	s_add_u32 s28, s74, 0x12da5c00
	s_addc_u32 s29, s75, 0
	v_mov_b32_e32 v116, v174
	s_cmpk_gt_i32 s2, 0x7ff
	s_barrier
	s_cbranch_scc1 .LBB0_300
	v_and_b32_e32 v196, 63, v174
	v_lshrrev_b32_e32 v197, 6, v174
	v_and_b32_e32 v198, 31, v196
	v_lshrrev_b32_e32 v199, 5, v196
	s_and_b32 s80, s2, 7
	v_lshl_add_u32 v200, s80, 3, v197
	v_lshl_add_u32 v201, v200, 6, v198
	v_lshlrev_b32_e32 v202, 6, v201
	v_lshl_add_u32 v202, v199, 5, v202
	global_load_dwordx4 v[24:27], v202, s[24:25] offset:0
	global_load_dwordx4 v[28:31], v202, s[24:25] offset:16
	global_load_dwordx4 v[40:43], v202, s[24:25] offset:2048
	global_load_dwordx4 v[44:47], v202, s[24:25] offset:2064
	global_load_dwordx4 v[32:35], v202, s[26:27] offset:0
	global_load_dwordx4 v[36:39], v202, s[26:27] offset:16
	global_load_dwordx4 v[48:51], v202, s[26:27] offset:2048
	global_load_dwordx4 v[52:55], v202, s[26:27] offset:2064
	v_lshlrev_b32_e32 v203, 3, v201
	s_lshl_b32 s81, s80, 7
	v_lshl_add_u32 v204, v197, 4, s81
	v_lshl_add_u32 v204, v199, 3, v204
	v_lshlrev_b32_e32 v204, 2, v204
	global_load_dwordx4 v[140:143], v204, s[42:43]
	global_load_dwordx4 v[144:147], v204, s[42:43] offset:16
	v_lshl_add_u32 v205, v198, 12, v204
	v_lshlrev_b32_e32 v206, 2, v198
	v_lshl_add_u32 v207, v200, 6, v196
	v_lshlrev_b32_e32 v207, 3, v207
	v_mov_b32_e32 v208, 0x358637bd
	s_mov_b32 s8, 0
	s_mov_b32 s9, -1
	global_load_dwordx2 v[0:1], v203, s[10:11]
	global_load_dwordx2 v[2:3], v203, s[10:11] offset:256
	s_waitcnt vmcnt(0)
	v_mul_f32_e32 v58, v1, v1
	v_mul_f32_e32 v59, v1, v0
	v_fma_f32 v4, v0, v0, -v58
	v_fma_f32 v5, v0, v1, v59
	v_mul_f32_e32 v128, v3, v3
	v_mul_f32_e32 v129, v3, v2
	v_fma_f32 v6, v2, v2, -v128
	v_fma_f32 v7, v2, v3, v129
	v_mul_f32_e32 v58, v5, v5
	v_mul_f32_e32 v59, v5, v4
	v_fma_f32 v8, v4, v4, -v58
	v_fma_f32 v9, v4, v5, v59
	v_mul_f32_e32 v128, v7, v7
	v_mul_f32_e32 v129, v7, v6
	v_fma_f32 v10, v6, v6, -v128
	v_fma_f32 v11, v6, v7, v129
	v_mul_f32_e32 v58, v9, v9
	v_mul_f32_e32 v59, v9, v8
	v_fma_f32 v14, v8, v8, -v58
	v_fma_f32 v15, v8, v9, v59
	v_mul_f32_e32 v128, v11, v11
	v_mul_f32_e32 v129, v11, v10
	v_fma_f32 v16, v10, v10, -v128
	v_fma_f32 v17, v10, v11, v129
	s_mov_b32 s82, s2
	s_lshr_b32 s4, s82, 10
	s_bfe_u32 s6, s82, 0x70003
	s_lshl_b32 s4, s4, 13
	s_lshl_b32 s6, s6, 6
	s_add_i32 s31, s4, s6
	s_lshl_b32 s6, s31, 12
	s_add_u32 s84, s38, s6
	s_addc_u32 s85, s39, 0
	s_add_u32 s88, s84, 0x20000
	s_addc_u32 s89, s85, 0
	s_lshl_b32 s6, s31, 2
	s_add_u32 s86, s22, s6
	s_addc_u32 s87, s23, 0
	global_load_dwordx4 v[178:181], v205, s[84:85]
	global_load_dwordx4 v[182:185], v205, s[84:85] offset:16
	global_load_dword v194, v206, s[86:87]
	global_load_dwordx4 v[186:189], v205, s[88:89]
	global_load_dwordx4 v[190:193], v205, s[88:89] offset:16
	global_load_dword v195, v206, s[86:87] offset:128
.Ls5a_item:
	s_add_i32 s83, s82, 0x100
	s_cmpk_gt_i32 s83, 0x7ff
	s_cselect_b32 s83, s82, s83
	s_lshr_b32 s4, s83, 10
	s_bfe_u32 s6, s83, 0x70003
	s_lshl_b32 s4, s4, 13
	s_lshl_b32 s6, s6, 6
	s_add_i32 s32, s4, s6
	s_lshl_b32 s6, s32, 12
	s_add_u32 s90, s38, s6
	s_addc_u32 s91, s39, 0
	s_add_u32 s94, s90, 0x20000
	s_addc_u32 s95, s91, 0
	s_lshl_b32 s6, s32, 2
	s_add_u32 s92, s22, s6
	s_addc_u32 s93, s23, 0
	v_mov_b32_e32 v18, 0
	v_mov_b32_e32 v19, 0
	v_mov_b32_e32 v22, 0
	v_mov_b32_e32 v23, 0
	s_waitcnt vmcnt(3)
	v_fmamk_f32 v56, v194, 0x3a800000, v208
	v_rsq_f32_e32 v56, v56
	s_nop 0
	v_pk_mul_f32 v[148:149], v[178:179], v[56:57] op_sel_hi:[1,0]
	v_pk_mul_f32 v[150:151], v[180:181], v[56:57] op_sel_hi:[1,0]
	v_pk_mul_f32 v[152:153], v[182:183], v[56:57] op_sel_hi:[1,0]
	v_pk_mul_f32 v[154:155], v[184:185], v[56:57] op_sel_hi:[1,0]
	v_pk_mul_f32 v[148:149], v[140:141], v[148:149]
	v_pk_mul_f32 v[150:151], v[142:143], v[150:151]
	v_pk_mul_f32 v[152:153], v[144:145], v[152:153]
	v_pk_mul_f32 v[154:155], v[146:147], v[154:155]
	global_load_dwordx4 v[178:181], v205, s[90:91]
	global_load_dwordx4 v[182:185], v205, s[90:91] offset:16
	global_load_dword v194, v206, s[92:93]
	s_nop 1
	v_mfma_f32_32x32x2_f32 v[64:79], v148, v24, 0
	v_mfma_f32_32x32x2_f32 v[80:95], v148, v32, 0
	v_mfma_f32_32x32x2_f32 v[96:111], v148, v40, 0
	v_mfma_f32_32x32x2_f32 v[112:127], v148, v48, 0
	v_mfma_f32_32x32x2_f32 v[64:79], v149, v25, v[64:79]
	v_mfma_f32_32x32x2_f32 v[80:95], v149, v33, v[80:95]
	v_mfma_f32_32x32x2_f32 v[96:111], v149, v41, v[96:111]
	v_mfma_f32_32x32x2_f32 v[112:127], v149, v49, v[112:127]
	v_mfma_f32_32x32x2_f32 v[64:79], v150, v26, v[64:79]
	v_mfma_f32_32x32x2_f32 v[80:95], v150, v34, v[80:95]
	v_mfma_f32_32x32x2_f32 v[96:111], v150, v42, v[96:111]
	v_mfma_f32_32x32x2_f32 v[112:127], v150, v50, v[112:127]
	v_mfma_f32_32x32x2_f32 v[64:79], v151, v27, v[64:79]
	v_mfma_f32_32x32x2_f32 v[80:95], v151, v35, v[80:95]
	v_mfma_f32_32x32x2_f32 v[96:111], v151, v43, v[96:111]
	v_mfma_f32_32x32x2_f32 v[112:127], v151, v51, v[112:127]
	v_mfma_f32_32x32x2_f32 v[64:79], v152, v28, v[64:79]
	v_mfma_f32_32x32x2_f32 v[80:95], v152, v36, v[80:95]
	v_mfma_f32_32x32x2_f32 v[96:111], v152, v44, v[96:111]
	v_mfma_f32_32x32x2_f32 v[112:127], v152, v52, v[112:127]
	v_mfma_f32_32x32x2_f32 v[64:79], v153, v29, v[64:79]
	v_mfma_f32_32x32x2_f32 v[80:95], v153, v37, v[80:95]
	v_mfma_f32_32x32x2_f32 v[96:111], v153, v45, v[96:111]
	v_mfma_f32_32x32x2_f32 v[112:127], v153, v53, v[112:127]
	v_mfma_f32_32x32x2_f32 v[64:79], v154, v30, v[64:79]
	v_mfma_f32_32x32x2_f32 v[80:95], v154, v38, v[80:95]
	v_mfma_f32_32x32x2_f32 v[96:111], v154, v46, v[96:111]
	v_mfma_f32_32x32x2_f32 v[112:127], v154, v54, v[112:127]
	v_mfma_f32_32x32x2_f32 v[64:79], v155, v31, v[64:79]
	v_mfma_f32_32x32x2_f32 v[80:95], v155, v39, v[80:95]
	v_mfma_f32_32x32x2_f32 v[96:111], v155, v47, v[96:111]
	v_mfma_f32_32x32x2_f32 v[112:127], v155, v55, v[112:127]
	s_nop 7
	s_nop 7
	s_nop 1
	v_fma_f32 v58, v64, v0, v65
	v_fma_f32 v59, v64, v1, v81
	v_fma_f32 v65, -v80, v1, v58
	v_fma_f32 v81, v80, v0, v59
	v_fma_f32 v128, v96, v2, v97
	v_fma_f32 v129, v96, v3, v113
	v_fma_f32 v97, -v112, v3, v128
	v_fma_f32 v113, v112, v2, v129
	v_fma_f32 v58, v68, v0, v69
	v_fma_f32 v59, v68, v1, v85
	v_fma_f32 v69, -v84, v1, v58
	v_fma_f32 v85, v84, v0, v59
	v_fma_f32 v128, v100, v2, v101
	v_fma_f32 v129, v100, v3, v117
	v_fma_f32 v101, -v116, v3, v128
	v_fma_f32 v117, v116, v2, v129
	v_fma_f32 v58, v72, v0, v73
	v_fma_f32 v59, v72, v1, v89
	v_fma_f32 v73, -v88, v1, v58
	v_fma_f32 v89, v88, v0, v59
	v_fma_f32 v128, v104, v2, v105
	v_fma_f32 v129, v104, v3, v121
	v_fma_f32 v105, -v120, v3, v128
	v_fma_f32 v121, v120, v2, v129
	v_fma_f32 v58, v76, v0, v77
	v_fma_f32 v59, v76, v1, v93
	v_fma_f32 v77, -v92, v1, v58
	v_fma_f32 v93, v92, v0, v59
	v_fma_f32 v128, v108, v2, v109
	v_fma_f32 v129, v108, v3, v125
	v_fma_f32 v109, -v124, v3, v128
	v_fma_f32 v125, v124, v2, v129
	v_fma_f32 v58, v65, v0, v66
	v_fma_f32 v59, v65, v1, v82
	v_fma_f32 v66, -v81, v1, v58
	v_fma_f32 v82, v81, v0, v59
	v_fma_f32 v128, v97, v2, v98
	v_fma_f32 v129, v97, v3, v114
	v_fma_f32 v98, -v113, v3, v128
	v_fma_f32 v114, v113, v2, v129
	v_fma_f32 v58, v69, v0, v70
	v_fma_f32 v59, v69, v1, v86
	v_fma_f32 v70, -v85, v1, v58
	v_fma_f32 v86, v85, v0, v59
	v_fma_f32 v128, v101, v2, v102
	v_fma_f32 v129, v101, v3, v118
	v_fma_f32 v102, -v117, v3, v128
	v_fma_f32 v118, v117, v2, v129
	v_fma_f32 v58, v73, v0, v74
	v_fma_f32 v59, v73, v1, v90
	v_fma_f32 v74, -v89, v1, v58
	v_fma_f32 v90, v89, v0, v59
	v_fma_f32 v128, v105, v2, v106
	v_fma_f32 v129, v105, v3, v122
	v_fma_f32 v106, -v121, v3, v128
	v_fma_f32 v122, v121, v2, v129
	v_fma_f32 v58, v77, v0, v78
	v_fma_f32 v59, v77, v1, v94
	v_fma_f32 v78, -v93, v1, v58
	v_fma_f32 v94, v93, v0, v59
	v_fma_f32 v128, v109, v2, v110
	v_fma_f32 v129, v109, v3, v126
	v_fma_f32 v110, -v125, v3, v128
	v_fma_f32 v126, v125, v2, v129
	v_fma_f32 v58, v66, v0, v67
	v_fma_f32 v59, v66, v1, v83
	v_fma_f32 v67, -v82, v1, v58
	v_fma_f32 v83, v82, v0, v59
	v_fma_f32 v128, v98, v2, v99
	v_fma_f32 v129, v98, v3, v115
	v_fma_f32 v99, -v114, v3, v128
	v_fma_f32 v115, v114, v2, v129
	v_fma_f32 v58, v70, v0, v71
	v_fma_f32 v59, v70, v1, v87
	v_fma_f32 v71, -v86, v1, v58
	v_fma_f32 v87, v86, v0, v59
	v_fma_f32 v128, v102, v2, v103
	v_fma_f32 v129, v102, v3, v119
	v_fma_f32 v103, -v118, v3, v128
	v_fma_f32 v119, v118, v2, v129
	v_fma_f32 v58, v74, v0, v75
	v_fma_f32 v59, v74, v1, v91
	v_fma_f32 v75, -v90, v1, v58
	v_fma_f32 v91, v90, v0, v59
	v_fma_f32 v128, v106, v2, v107
	v_fma_f32 v129, v106, v3, v123
	v_fma_f32 v107, -v122, v3, v128
	v_fma_f32 v123, v122, v2, v129
	v_fma_f32 v58, v78, v0, v79
	v_fma_f32 v59, v78, v1, v95
	v_fma_f32 v79, -v94, v1, v58
	v_fma_f32 v95, v94, v0, v59
	v_fma_f32 v128, v110, v2, v111
	v_fma_f32 v129, v110, v3, v127
	v_fma_f32 v111, -v126, v3, v128
	v_fma_f32 v127, v126, v2, v129
	v_fma_f32 v58, v18, v14, v67
	v_fma_f32 v59, v18, v15, v83
	v_fma_f32 v18, -v19, v15, v58
	v_fma_f32 v19, v19, v14, v59
	v_fma_f32 v128, v22, v16, v99
	v_fma_f32 v129, v22, v17, v115
	v_fma_f32 v22, -v23, v17, v128
	v_fma_f32 v23, v23, v16, v129
	v_fma_f32 v58, v18, v14, v71
	v_fma_f32 v59, v18, v15, v87
	v_fma_f32 v18, -v19, v15, v58
	v_fma_f32 v19, v19, v14, v59
	v_fma_f32 v128, v22, v16, v103
	v_fma_f32 v129, v22, v17, v119
	v_fma_f32 v22, -v23, v17, v128
	v_fma_f32 v23, v23, v16, v129
	v_fma_f32 v58, v18, v14, v75
	v_fma_f32 v59, v18, v15, v91
	v_fma_f32 v18, -v19, v15, v58
	v_fma_f32 v19, v19, v14, v59
	v_fma_f32 v128, v22, v16, v107
	v_fma_f32 v129, v22, v17, v123
	v_fma_f32 v22, -v23, v17, v128
	v_fma_f32 v23, v23, v16, v129
	v_fma_f32 v58, v18, v14, v79
	v_fma_f32 v59, v18, v15, v95
	v_fma_f32 v18, -v19, v15, v58
	v_fma_f32 v19, v19, v14, v59
	v_fma_f32 v128, v22, v16, v111
	v_fma_f32 v129, v22, v17, v127
	v_fma_f32 v22, -v23, v17, v128
	v_fma_f32 v23, v23, v16, v129
	s_waitcnt vmcnt(3)
	v_fmamk_f32 v56, v195, 0x3a800000, v208
	v_rsq_f32_e32 v56, v56
	s_nop 0
	v_pk_mul_f32 v[148:149], v[186:187], v[56:57] op_sel_hi:[1,0]
	v_pk_mul_f32 v[150:151], v[188:189], v[56:57] op_sel_hi:[1,0]
	v_pk_mul_f32 v[152:153], v[190:191], v[56:57] op_sel_hi:[1,0]
	v_pk_mul_f32 v[154:155], v[192:193], v[56:57] op_sel_hi:[1,0]
	v_pk_mul_f32 v[148:149], v[140:141], v[148:149]
	v_pk_mul_f32 v[150:151], v[142:143], v[150:151]
	v_pk_mul_f32 v[152:153], v[144:145], v[152:153]
	v_pk_mul_f32 v[154:155], v[146:147], v[154:155]
	global_load_dwordx4 v[186:189], v205, s[94:95]
	global_load_dwordx4 v[190:193], v205, s[94:95] offset:16
	global_load_dword v195, v206, s[92:93] offset:128
	s_nop 1
	v_mfma_f32_32x32x2_f32 v[64:79], v148, v24, 0
	v_mfma_f32_32x32x2_f32 v[80:95], v148, v32, 0
	v_mfma_f32_32x32x2_f32 v[96:111], v148, v40, 0
	v_mfma_f32_32x32x2_f32 v[112:127], v148, v48, 0
	v_mfma_f32_32x32x2_f32 v[64:79], v149, v25, v[64:79]
	v_mfma_f32_32x32x2_f32 v[80:95], v149, v33, v[80:95]
	v_mfma_f32_32x32x2_f32 v[96:111], v149, v41, v[96:111]
	v_mfma_f32_32x32x2_f32 v[112:127], v149, v49, v[112:127]
	v_mfma_f32_32x32x2_f32 v[64:79], v150, v26, v[64:79]
	v_mfma_f32_32x32x2_f32 v[80:95], v150, v34, v[80:95]
	v_mfma_f32_32x32x2_f32 v[96:111], v150, v42, v[96:111]
	v_mfma_f32_32x32x2_f32 v[112:127], v150, v50, v[112:127]
	v_mfma_f32_32x32x2_f32 v[64:79], v151, v27, v[64:79]
	v_mfma_f32_32x32x2_f32 v[80:95], v151, v35, v[80:95]
	v_mfma_f32_32x32x2_f32 v[96:111], v151, v43, v[96:111]
	v_mfma_f32_32x32x2_f32 v[112:127], v151, v51, v[112:127]
	v_mfma_f32_32x32x2_f32 v[64:79], v152, v28, v[64:79]
	v_mfma_f32_32x32x2_f32 v[80:95], v152, v36, v[80:95]
	v_mfma_f32_32x32x2_f32 v[96:111], v152, v44, v[96:111]
	v_mfma_f32_32x32x2_f32 v[112:127], v152, v52, v[112:127]
	v_mfma_f32_32x32x2_f32 v[64:79], v153, v29, v[64:79]
	v_mfma_f32_32x32x2_f32 v[80:95], v153, v37, v[80:95]
	v_mfma_f32_32x32x2_f32 v[96:111], v153, v45, v[96:111]
	v_mfma_f32_32x32x2_f32 v[112:127], v153, v53, v[112:127]
	v_mfma_f32_32x32x2_f32 v[64:79], v154, v30, v[64:79]
	v_mfma_f32_32x32x2_f32 v[80:95], v154, v38, v[80:95]
	v_mfma_f32_32x32x2_f32 v[96:111], v154, v46, v[96:111]
	v_mfma_f32_32x32x2_f32 v[112:127], v154, v54, v[112:127]
	v_mfma_f32_32x32x2_f32 v[64:79], v155, v31, v[64:79]
	v_mfma_f32_32x32x2_f32 v[80:95], v155, v39, v[80:95]
	v_mfma_f32_32x32x2_f32 v[96:111], v155, v47, v[96:111]
	v_mfma_f32_32x32x2_f32 v[112:127], v155, v55, v[112:127]
	s_nop 7
	s_nop 7
	s_nop 1
	v_fma_f32 v58, v64, v0, v65
	v_fma_f32 v59, v64, v1, v81
	v_fma_f32 v65, -v80, v1, v58
	v_fma_f32 v81, v80, v0, v59
	v_fma_f32 v128, v96, v2, v97
	v_fma_f32 v129, v96, v3, v113
	v_fma_f32 v97, -v112, v3, v128
	v_fma_f32 v113, v112, v2, v129
	v_fma_f32 v58, v68, v0, v69
	v_fma_f32 v59, v68, v1, v85
	v_fma_f32 v69, -v84, v1, v58
	v_fma_f32 v85, v84, v0, v59
	v_fma_f32 v128, v100, v2, v101
	v_fma_f32 v129, v100, v3, v117
	v_fma_f32 v101, -v116, v3, v128
	v_fma_f32 v117, v116, v2, v129
	v_fma_f32 v58, v72, v0, v73
	v_fma_f32 v59, v72, v1, v89
	v_fma_f32 v73, -v88, v1, v58
	v_fma_f32 v89, v88, v0, v59
	v_fma_f32 v128, v104, v2, v105
	v_fma_f32 v129, v104, v3, v121
	v_fma_f32 v105, -v120, v3, v128
	v_fma_f32 v121, v120, v2, v129
	v_fma_f32 v58, v76, v0, v77
	v_fma_f32 v59, v76, v1, v93
	v_fma_f32 v77, -v92, v1, v58
	v_fma_f32 v93, v92, v0, v59
	v_fma_f32 v128, v108, v2, v109
	v_fma_f32 v129, v108, v3, v125
	v_fma_f32 v109, -v124, v3, v128
	v_fma_f32 v125, v124, v2, v129
	v_fma_f32 v58, v65, v0, v66
	v_fma_f32 v59, v65, v1, v82
	v_fma_f32 v66, -v81, v1, v58
	v_fma_f32 v82, v81, v0, v59
	v_fma_f32 v128, v97, v2, v98
	v_fma_f32 v129, v97, v3, v114
	v_fma_f32 v98, -v113, v3, v128
	v_fma_f32 v114, v113, v2, v129
	v_fma_f32 v58, v69, v0, v70
	v_fma_f32 v59, v69, v1, v86
	v_fma_f32 v70, -v85, v1, v58
	v_fma_f32 v86, v85, v0, v59
	v_fma_f32 v128, v101, v2, v102
	v_fma_f32 v129, v101, v3, v118
	v_fma_f32 v102, -v117, v3, v128
	v_fma_f32 v118, v117, v2, v129
	v_fma_f32 v58, v73, v0, v74
	v_fma_f32 v59, v73, v1, v90
	v_fma_f32 v74, -v89, v1, v58
	v_fma_f32 v90, v89, v0, v59
	v_fma_f32 v128, v105, v2, v106
	v_fma_f32 v129, v105, v3, v122
	v_fma_f32 v106, -v121, v3, v128
	v_fma_f32 v122, v121, v2, v129
	v_fma_f32 v58, v77, v0, v78
	v_fma_f32 v59, v77, v1, v94
	v_fma_f32 v78, -v93, v1, v58
	v_fma_f32 v94, v93, v0, v59
	v_fma_f32 v128, v109, v2, v110
	v_fma_f32 v129, v109, v3, v126
	v_fma_f32 v110, -v125, v3, v128
	v_fma_f32 v126, v125, v2, v129
	v_fma_f32 v58, v66, v0, v67
	v_fma_f32 v59, v66, v1, v83
	v_fma_f32 v67, -v82, v1, v58
	v_fma_f32 v83, v82, v0, v59
	v_fma_f32 v128, v98, v2, v99
	v_fma_f32 v129, v98, v3, v115
	v_fma_f32 v99, -v114, v3, v128
	v_fma_f32 v115, v114, v2, v129
	v_fma_f32 v58, v70, v0, v71
	v_fma_f32 v59, v70, v1, v87
	v_fma_f32 v71, -v86, v1, v58
	v_fma_f32 v87, v86, v0, v59
	v_fma_f32 v128, v102, v2, v103
	v_fma_f32 v129, v102, v3, v119
	v_fma_f32 v103, -v118, v3, v128
	v_fma_f32 v119, v118, v2, v129
	v_fma_f32 v58, v74, v0, v75
	v_fma_f32 v59, v74, v1, v91
	v_fma_f32 v75, -v90, v1, v58
	v_fma_f32 v91, v90, v0, v59
	v_fma_f32 v128, v106, v2, v107
	v_fma_f32 v129, v106, v3, v123
	v_fma_f32 v107, -v122, v3, v128
	v_fma_f32 v123, v122, v2, v129
	v_fma_f32 v58, v78, v0, v79
	v_fma_f32 v59, v78, v1, v95
	v_fma_f32 v79, -v94, v1, v58
	v_fma_f32 v95, v94, v0, v59
	v_fma_f32 v128, v110, v2, v111
	v_fma_f32 v129, v110, v3, v127
	v_fma_f32 v111, -v126, v3, v128
	v_fma_f32 v127, v126, v2, v129
	v_fma_f32 v58, v18, v14, v67
	v_fma_f32 v59, v18, v15, v83
	v_fma_f32 v18, -v19, v15, v58
	v_fma_f32 v19, v19, v14, v59
	v_fma_f32 v128, v22, v16, v99
	v_fma_f32 v129, v22, v17, v115
	v_fma_f32 v22, -v23, v17, v128
	v_fma_f32 v23, v23, v16, v129
	v_fma_f32 v58, v18, v14, v71
	v_fma_f32 v59, v18, v15, v87
	v_fma_f32 v18, -v19, v15, v58
	v_fma_f32 v19, v19, v14, v59
	v_fma_f32 v128, v22, v16, v103
	v_fma_f32 v129, v22, v17, v119
	v_fma_f32 v22, -v23, v17, v128
	v_fma_f32 v23, v23, v16, v129
	v_fma_f32 v58, v18, v14, v75
	v_fma_f32 v59, v18, v15, v91
	v_fma_f32 v18, -v19, v15, v58
	v_fma_f32 v19, v19, v14, v59
	v_fma_f32 v128, v22, v16, v107
	v_fma_f32 v129, v22, v17, v123
	v_fma_f32 v22, -v23, v17, v128
	v_fma_f32 v23, v23, v16, v129
	v_fma_f32 v58, v18, v14, v79
	v_fma_f32 v59, v18, v15, v95
	v_fma_f32 v18, -v19, v15, v58
	v_fma_f32 v19, v19, v14, v59
	v_fma_f32 v128, v22, v16, v111
	v_fma_f32 v129, v22, v17, v127
	v_fma_f32 v22, -v23, v17, v128
	v_fma_f32 v23, v23, v16, v129
	v_mov_b32_e32 v130, v18
	v_mov_b32_e32 v131, v19
	v_mov_b32_e32 v132, v22
	v_mov_b32_e32 v133, v23
	s_nop 1
	v_permlane32_swap_b32_e32 v18, v130
	v_permlane32_swap_b32_e32 v19, v131
	v_permlane32_swap_b32_e32 v22, v132
	v_permlane32_swap_b32_e32 v23, v133
	v_fma_f32 v58, v18, v8, v130
	v_fma_f32 v59, v18, v9, v131
	v_fma_f32 v134, -v19, v9, v58
	v_fma_f32 v135, v19, v8, v59
	v_fma_f32 v128, v22, v10, v132
	v_fma_f32 v129, v22, v11, v133
	v_fma_f32 v136, -v23, v11, v128
	v_fma_f32 v137, v23, v10, v129
	v_cndmask_b32_e64 v134, v134, v136, s[8:9]
	v_cndmask_b32_e64 v135, v135, v137, s[8:9]
	s_lshr_b32 s4, s82, 3
	s_lshl_b32 s4, s4, 15
	s_add_u32 s6, s28, s4
	s_addc_u32 s7, s29, 0
	global_store_dwordx2 v207, v[134:135], s[6:7]
	s_add_i32 s82, s82, 0x100
	s_cmpk_lt_i32 s82, 0x800
	s_cbranch_scc1 .Ls5a_item
